# E_RES GEMM epilogue (all but the first phase): X loads run three row-subtiles ahead of the update/store stream instead of 4 load-wait-store round trips
# speedup vs baseline: 1.0053x; 1.0053x over previous
.LBB0_1047:
	s_andn2_b64 vcc, exec, s[2:3]
	s_cbranch_vccnz .LBB0_632
	s_cmp_lt_i32 s44, 2
	s_mov_b64 s[2:3], -1
	s_cbranch_scc1 .LBB0_1217
	s_cmp_gt_i32 s44, 2
	s_cbranch_scc0 .LBB0_1086
	s_mul_hi_i32 s3, s45, 0x78787879
	s_lshr_b32 s4, s3, 31
	s_ashr_i32 s3, s3, 11
	s_add_i32 s3, s3, s4
	s_mul_i32 s4, s3, 0xffffef00
	s_add_i32 s4, s4, s45
	s_cmpk_gt_i32 s4, 0xff
	s_mul_i32 s2, s28, 9
	s_cselect_b32 s3, s3, 8
	s_add_i32 s2, s3, s2
	v_readlane_b32 s48, v254, 55
	s_mul_hi_i32 s3, s2, 0x6000
	s_mulk_i32 s2, 0x6000
	v_readlane_b32 s56, v254, 63
	v_readlane_b32 s57, v255, 0
	s_add_u32 s4, s56, s2
	s_mul_i32 s34, s29, 0xc00
	s_addc_u32 s5, s57, s3
	s_lshl_b64 s[2:3], s[34:35], 2
	s_add_u32 s4, s4, s2
	s_addc_u32 s5, s5, s3
	s_lshl_b64 s[2:3], s[6:7], 2
	s_add_u32 s4, s4, s2
	s_addc_u32 s5, s5, s3
	v_lshlrev_b32_e32 v0, 2, v224
	s_waitcnt vmcnt(0)
	v_lshl_add_u64 v[130:131], s[4:5], 0, v[0:1]
	v_lshlrev_b32_e32 v132, 4, v223
	v_mov_b32_e32 v133, v1
	v_lshl_add_u64 v[130:131], v[130:131], 0, v[132:133]
	s_mov_b64 s[4:5], 0x2000
	v_lshl_add_u64 v[132:133], v[130:131], 0, s[4:5]
	v_add_co_u32_e32 v130, vcc, 0x2000, v130
	s_or_b32 s4, s28, s29
	s_nop 0
	v_addc_co_u32_e32 v131, vcc, 0, v131, vcc
	global_load_dwordx4 v[138:141], v[132:133], off offset:64
	global_load_dwordx4 v[134:137], v[132:133], off offset:128
	global_load_dwordx4 v[142:145], v[130:131], off
	s_nop 0
	global_load_dwordx4 v[130:133], v[132:133], off offset:192
	s_cmp_lg_u32 s4, 0
	s_cselect_b64 s[28:29], -1, 0
	v_add_u32_e32 v166, s45, v225
	s_and_b64 vcc, exec, s[28:29]
	v_ashrrev_i32_e32 v167, 31, v166
	v_readlane_b32 s49, v254, 56
	v_readlane_b32 s50, v254, 57
	v_readlane_b32 s51, v254, 58
	v_readlane_b32 s52, v254, 59
	v_readlane_b32 s53, v254, 60
	v_readlane_b32 s54, v254, 61
	v_readlane_b32 s55, v254, 62
	v_readlane_b32 s58, v255, 1
	v_readlane_b32 s59, v255, 2
	v_readlane_b32 s60, v255, 3
	v_readlane_b32 s61, v255, 4
	v_readlane_b32 s62, v255, 5
	v_readlane_b32 s63, v255, 6
	s_cbranch_vccz .LBB0_1052
	v_readlane_b32 s52, v254, 59
	v_readlane_b32 s53, v254, 60
	v_lshlrev_b64 v[146:147], 12, v[166:167]
	v_lshlrev_b32_e32 v148, 4, v223
	v_mov_b32_e32 v149, 0
	v_lshl_add_u64 v[146:147], v[146:147], 0, s[2:3]
	v_lshl_add_u64 v[146:147], v[146:147], 0, v[0:1]
	v_lshl_add_u64 v[146:147], v[146:147], 0, v[148:149]
	v_lshl_add_u64 v[146:147], s[52:53], 0, v[146:147]
	v_mov_b32_e32 v150, v146
	v_mov_b32_e32 v151, v147
	s_mov_b32 s14, 0x10000
	s_mov_b32 s15, 0
	global_load_dwordx4 v[152:155], v[146:147], off
	global_load_dwordx4 v[156:159], v[146:147], off offset:64
	global_load_dwordx4 v[164:167], v[146:147], off offset:128
	global_load_dwordx4 v[168:171], v[146:147], off offset:192
	v_lshl_add_u64 v[146:147], v[146:147], 0, s[14:15]
	global_load_dwordx4 v[172:175], v[146:147], off
	global_load_dwordx4 v[176:179], v[146:147], off offset:64
	global_load_dwordx4 v[180:183], v[146:147], off offset:128
	global_load_dwordx4 v[184:187], v[146:147], off offset:192
	v_lshl_add_u64 v[146:147], v[146:147], 0, s[14:15]
	global_load_dwordx4 v[200:203], v[146:147], off
	global_load_dwordx4 v[228:231], v[146:147], off offset:64
	global_load_dwordx4 v[232:235], v[146:147], off offset:128
	global_load_dwordx4 v[236:239], v[146:147], off offset:192
	v_lshl_add_u64 v[146:147], v[146:147], 0, s[14:15]
	s_waitcnt vmcnt(8)
	v_pk_fma_f32 v[152:153], v[126:127], v[142:143], v[152:153]
	v_pk_fma_f32 v[154:155], v[128:129], v[144:145], v[154:155]
	v_pk_fma_f32 v[156:157], v[122:123], v[138:139], v[156:157]
	v_pk_fma_f32 v[158:159], v[124:125], v[140:141], v[158:159]
	v_pk_fma_f32 v[164:165], v[118:119], v[134:135], v[164:165]
	v_pk_fma_f32 v[166:167], v[120:121], v[136:137], v[166:167]
	v_pk_fma_f32 v[168:169], v[114:115], v[130:131], v[168:169]
	v_pk_fma_f32 v[170:171], v[116:117], v[132:133], v[170:171]
	global_store_dwordx4 v[150:151], v[152:155], off
	global_store_dwordx4 v[150:151], v[156:159], off offset:64
	global_store_dwordx4 v[150:151], v[164:167], off offset:128
	global_store_dwordx4 v[150:151], v[168:171], off offset:192
	v_lshl_add_u64 v[150:151], v[150:151], 0, s[14:15]
	global_load_dwordx4 v[152:155], v[146:147], off
	global_load_dwordx4 v[156:159], v[146:147], off offset:64
	global_load_dwordx4 v[164:167], v[146:147], off offset:128
	global_load_dwordx4 v[168:171], v[146:147], off offset:192
	v_lshl_add_u64 v[146:147], v[146:147], 0, s[14:15]
	s_waitcnt vmcnt(12)
	v_pk_fma_f32 v[172:173], v[110:111], v[142:143], v[172:173]
	v_pk_fma_f32 v[174:175], v[112:113], v[144:145], v[174:175]
	v_pk_fma_f32 v[176:177], v[106:107], v[138:139], v[176:177]
	v_pk_fma_f32 v[178:179], v[108:109], v[140:141], v[178:179]
	v_pk_fma_f32 v[180:181], v[102:103], v[134:135], v[180:181]
	v_pk_fma_f32 v[182:183], v[104:105], v[136:137], v[182:183]
	v_pk_fma_f32 v[184:185], v[98:99], v[130:131], v[184:185]
	v_pk_fma_f32 v[186:187], v[100:101], v[132:133], v[186:187]
	global_store_dwordx4 v[150:151], v[172:175], off
	global_store_dwordx4 v[150:151], v[176:179], off offset:64
	global_store_dwordx4 v[150:151], v[180:183], off offset:128
	global_store_dwordx4 v[150:151], v[184:187], off offset:192
	v_lshl_add_u64 v[150:151], v[150:151], 0, s[14:15]
	global_load_dwordx4 v[172:175], v[146:147], off
	global_load_dwordx4 v[176:179], v[146:147], off offset:64
	global_load_dwordx4 v[180:183], v[146:147], off offset:128
	global_load_dwordx4 v[184:187], v[146:147], off offset:192
	v_lshl_add_u64 v[146:147], v[146:147], 0, s[14:15]
	s_waitcnt vmcnt(16)
	v_pk_fma_f32 v[200:201], v[94:95], v[142:143], v[200:201]
	v_pk_fma_f32 v[202:203], v[96:97], v[144:145], v[202:203]
	v_pk_fma_f32 v[228:229], v[90:91], v[138:139], v[228:229]
	v_pk_fma_f32 v[230:231], v[92:93], v[140:141], v[230:231]
	v_pk_fma_f32 v[232:233], v[86:87], v[134:135], v[232:233]
	v_pk_fma_f32 v[234:235], v[88:89], v[136:137], v[234:235]
	v_pk_fma_f32 v[236:237], v[82:83], v[130:131], v[236:237]
	v_pk_fma_f32 v[238:239], v[84:85], v[132:133], v[238:239]
	global_store_dwordx4 v[150:151], v[200:203], off
	global_store_dwordx4 v[150:151], v[228:231], off offset:64
	global_store_dwordx4 v[150:151], v[232:235], off offset:128
	global_store_dwordx4 v[150:151], v[236:239], off offset:192
	v_lshl_add_u64 v[150:151], v[150:151], 0, s[14:15]
	global_load_dwordx4 v[200:203], v[146:147], off
	global_load_dwordx4 v[228:231], v[146:147], off offset:64
	global_load_dwordx4 v[232:235], v[146:147], off offset:128
	global_load_dwordx4 v[236:239], v[146:147], off offset:192
	v_lshl_add_u64 v[146:147], v[146:147], 0, s[14:15]
	s_waitcnt vmcnt(16)
	v_pk_fma_f32 v[152:153], v[78:79], v[142:143], v[152:153]
	v_pk_fma_f32 v[154:155], v[80:81], v[144:145], v[154:155]
	v_pk_fma_f32 v[156:157], v[74:75], v[138:139], v[156:157]
	v_pk_fma_f32 v[158:159], v[76:77], v[140:141], v[158:159]
	v_pk_fma_f32 v[164:165], v[70:71], v[134:135], v[164:165]
	v_pk_fma_f32 v[166:167], v[72:73], v[136:137], v[166:167]
	v_pk_fma_f32 v[168:169], v[66:67], v[130:131], v[168:169]
	v_pk_fma_f32 v[170:171], v[68:69], v[132:133], v[170:171]
	global_store_dwordx4 v[150:151], v[152:155], off
	global_store_dwordx4 v[150:151], v[156:159], off offset:64
	global_store_dwordx4 v[150:151], v[164:167], off offset:128
	global_store_dwordx4 v[150:151], v[168:171], off offset:192
	v_lshl_add_u64 v[150:151], v[150:151], 0, s[14:15]
	global_load_dwordx4 v[152:155], v[146:147], off
	global_load_dwordx4 v[156:159], v[146:147], off offset:64
	global_load_dwordx4 v[164:167], v[146:147], off offset:128
	global_load_dwordx4 v[168:171], v[146:147], off offset:192
	v_lshl_add_u64 v[146:147], v[146:147], 0, s[14:15]
	s_waitcnt vmcnt(16)
	v_pk_fma_f32 v[172:173], v[62:63], v[142:143], v[172:173]
	v_pk_fma_f32 v[174:175], v[64:65], v[144:145], v[174:175]
	v_pk_fma_f32 v[176:177], v[58:59], v[138:139], v[176:177]
	v_pk_fma_f32 v[178:179], v[60:61], v[140:141], v[178:179]
	v_pk_fma_f32 v[180:181], v[54:55], v[134:135], v[180:181]
	v_pk_fma_f32 v[182:183], v[56:57], v[136:137], v[182:183]
	v_pk_fma_f32 v[184:185], v[50:51], v[130:131], v[184:185]
	v_pk_fma_f32 v[186:187], v[52:53], v[132:133], v[186:187]
	global_store_dwordx4 v[150:151], v[172:175], off
	global_store_dwordx4 v[150:151], v[176:179], off offset:64
	global_store_dwordx4 v[150:151], v[180:183], off offset:128
	global_store_dwordx4 v[150:151], v[184:187], off offset:192
	v_lshl_add_u64 v[150:151], v[150:151], 0, s[14:15]
	global_load_dwordx4 v[172:175], v[146:147], off
	global_load_dwordx4 v[176:179], v[146:147], off offset:64
	global_load_dwordx4 v[180:183], v[146:147], off offset:128
	global_load_dwordx4 v[184:187], v[146:147], off offset:192
	v_lshl_add_u64 v[146:147], v[146:147], 0, s[14:15]
	s_waitcnt vmcnt(16)
	v_pk_fma_f32 v[200:201], v[46:47], v[142:143], v[200:201]
	v_pk_fma_f32 v[202:203], v[48:49], v[144:145], v[202:203]
	v_pk_fma_f32 v[228:229], v[42:43], v[138:139], v[228:229]
	v_pk_fma_f32 v[230:231], v[44:45], v[140:141], v[230:231]
	v_pk_fma_f32 v[232:233], v[34:35], v[134:135], v[232:233]
	v_pk_fma_f32 v[234:235], v[36:37], v[136:137], v[234:235]
	v_pk_fma_f32 v[236:237], v[30:31], v[130:131], v[236:237]
	v_pk_fma_f32 v[238:239], v[32:33], v[132:133], v[238:239]
	global_store_dwordx4 v[150:151], v[200:203], off
	global_store_dwordx4 v[150:151], v[228:231], off offset:64
	global_store_dwordx4 v[150:151], v[232:235], off offset:128
	global_store_dwordx4 v[150:151], v[236:239], off offset:192
	v_lshl_add_u64 v[150:151], v[150:151], 0, s[14:15]
	s_waitcnt vmcnt(12)
	v_pk_fma_f32 v[152:153], v[38:39], v[142:143], v[152:153]
	v_pk_fma_f32 v[154:155], v[40:41], v[144:145], v[154:155]
	v_pk_fma_f32 v[156:157], v[26:27], v[138:139], v[156:157]
	v_pk_fma_f32 v[158:159], v[28:29], v[140:141], v[158:159]
	v_pk_fma_f32 v[164:165], v[22:23], v[134:135], v[164:165]
	v_pk_fma_f32 v[166:167], v[24:25], v[136:137], v[166:167]
	v_pk_fma_f32 v[168:169], v[18:19], v[130:131], v[168:169]
	v_pk_fma_f32 v[170:171], v[20:21], v[132:133], v[170:171]
	global_store_dwordx4 v[150:151], v[152:155], off
	global_store_dwordx4 v[150:151], v[156:159], off offset:64
	global_store_dwordx4 v[150:151], v[164:167], off offset:128
	global_store_dwordx4 v[150:151], v[168:171], off offset:192
	v_lshl_add_u64 v[150:151], v[150:151], 0, s[14:15]
	s_waitcnt vmcnt(8)
	v_pk_fma_f32 v[172:173], v[14:15], v[142:143], v[172:173]
	v_pk_fma_f32 v[174:175], v[16:17], v[144:145], v[174:175]
	v_pk_fma_f32 v[176:177], v[10:11], v[138:139], v[176:177]
	v_pk_fma_f32 v[178:179], v[12:13], v[140:141], v[178:179]
	v_pk_fma_f32 v[180:181], v[6:7], v[134:135], v[180:181]
	v_pk_fma_f32 v[182:183], v[8:9], v[136:137], v[182:183]
	v_pk_fma_f32 v[184:185], v[2:3], v[130:131], v[184:185]
	v_pk_fma_f32 v[186:187], v[4:5], v[132:133], v[186:187]
	global_store_dwordx4 v[150:151], v[172:175], off
	global_store_dwordx4 v[150:151], v[176:179], off offset:64
	global_store_dwordx4 v[150:151], v[180:183], off offset:128
	global_store_dwordx4 v[150:151], v[184:187], off offset:192
	v_lshl_add_u64 v[150:151], v[150:151], 0, s[14:15]
	s_mov_b64 s[2:3], 0
	s_branch .LBB0_1086
